# POOLEDS (pooled sample rows): all window loads issued up front then one wait, instead of up to 16 serialized load+wait round trips
# speedup vs baseline: 1.0084x; 1.0084x over previous
.LBB0_455:
	v_writelane_b32 v238, s14, 15
	s_nop 1
	v_writelane_b32 v238, s15, 16
	s_or_b64 exec, exec, s[8:9]
	s_add_u32 s8, s92, 0xdb00000
	s_mov_b32 s0, 0x8000
	s_addc_u32 s9, s93, 0
	v_cmp_gt_i32_e32 vcc, s0, v134
	s_and_saveexec_b64 s[10:11], vcc
	v_readlane_b32 s34, v239, 59
	v_readlane_b32 s56, v239, 61
	v_readlane_b32 s58, v239, 63
	v_readlane_b32 s62, v238, 1
	v_readlane_b32 s72, v238, 3
	v_readlane_b32 s74, v238, 5
	v_readlane_b32 s76, v238, 7
	v_readlane_b32 s82, v238, 9
	v_readlane_b32 s84, v238, 11
	v_readlane_b32 s35, v239, 60
	v_readlane_b32 s57, v239, 62
	v_readlane_b32 s59, v238, 0
	v_readlane_b32 s63, v238, 2
	v_readlane_b32 s73, v238, 4
	v_readlane_b32 s75, v238, 6
	v_readlane_b32 s77, v238, 8
	v_readlane_b32 s83, v238, 10
	v_readlane_b32 s85, v238, 12
	s_cbranch_execz .LBB0_498
	v_readfirstlane_b32 s0, v134
	v_and_b32_e32 v7, 0x3ff, v134
	v_ashrrev_i32_e32 v8, 12, v134
	v_ashrrev_i32_e32 v4, 10, v134
	s_bfe_u32 s1, s0, 0x2000a
	s_bfe_u32 s14, s0, 0x20008
	v_mov_b32_e32 v1, 0
	v_and_b32_e32 v0, 0xff, v134
	v_lshlrev_b32_e32 v0, 1, v0
	v_lshl_add_u64 v[2:3], s[8:9], 0, v[0:1]
	v_lshlrev_b32_e32 v0, 1, v7
	v_lshl_add_u64 v[10:11], s[28:29], 0, v[0:1]
	s_mov_b64 s[12:13], 0x2000
	v_lshl_add_u64 v[10:11], v[10:11], 0, s[12:13]
	v_lshlrev_b32_e32 v0, 2, v7
	v_lshl_add_u64 v[18:19], s[52:53], 0, v[0:1]
	v_and_b32_e32 v6, 3, v4
	v_lshlrev_b32_e32 v15, 2, v8
	v_add_u32_e32 v13, 0x2000, v15
	v_add_u32_e32 v13, v13, v6
	v_mul_u32_u24_e32 v9, 15, v8
	v_add3_u32 v9, v9, v6, 15
	v_mov_b32_e32 v20, 0
	v_mov_b32_e32 v21, 0
	v_mov_b32_e32 v22, 0
	v_mov_b32_e32 v23, 0
	v_mov_b32_e32 v17, 0
	v_mov_b32_e32 v37, 0
	v_mov_b32_e32 v16, v13
	v_lshl_add_u32 v16, v16, 1, v16
	v_lshlrev_b32_e32 v16, 12, v16
	v_lshl_add_u64 v[38:39], v[16:17], 0, v[10:11]
	global_load_short_d16_hi v20, v[38:39], off
	s_cmp_lt_u32 s1, 1
	s_cbranch_scc1 .Lpq_s1
	v_add_u32_e32 v36, -1, v13
	v_lshl_add_u32 v36, v36, 1, v36
	v_lshlrev_b32_e32 v36, 12, v36
	v_lshl_add_u64 v[40:41], v[36:37], 0, v[10:11]
	global_load_short_d16_hi v21, v[40:41], off
	s_branch .Lpq_d1
.Lpq_s1:
	v_add_u32_e32 v16, -1, v9
	v_lshlrev_b32_e32 v16, 12, v16
	v_lshl_add_u64 v[38:39], v[16:17], 0, v[18:19]
	global_load_dword v21, v[38:39], off
.Lpq_d1:
	s_cmp_eq_u32 s14, 0
	s_cbranch_scc1 .Lpq_issued
	s_cmp_lt_u32 s1, 2
	s_cbranch_scc1 .Lpq_s2
	v_add_u32_e32 v36, -2, v13
	v_lshl_add_u32 v36, v36, 1, v36
	v_lshlrev_b32_e32 v36, 12, v36
	v_lshl_add_u64 v[40:41], v[36:37], 0, v[10:11]
	global_load_short_d16_hi v22, v[40:41], off
	s_branch .Lpq_d2
.Lpq_s2:
	v_add_u32_e32 v16, -2, v9
	v_lshlrev_b32_e32 v16, 12, v16
	v_lshl_add_u64 v[38:39], v[16:17], 0, v[18:19]
	global_load_dword v22, v[38:39], off
.Lpq_d2:
	s_cmp_lt_u32 s1, 3
	s_cbranch_scc1 .Lpq_s3
	v_add_u32_e32 v36, -3, v13
	v_lshl_add_u32 v36, v36, 1, v36
	v_lshlrev_b32_e32 v36, 12, v36
	v_lshl_add_u64 v[40:41], v[36:37], 0, v[10:11]
	global_load_short_d16_hi v23, v[40:41], off
	s_branch .Lpq_d3
.Lpq_s3:
	v_add_u32_e32 v16, -3, v9
	v_lshlrev_b32_e32 v16, 12, v16
	v_lshl_add_u64 v[38:39], v[16:17], 0, v[18:19]
	global_load_dword v23, v[38:39], off
.Lpq_d3:
	s_cmp_lt_u32 s14, 2
	s_cbranch_scc1 .Lpq_issued
	v_add_u32_e32 v36, -4, v9
	v_lshlrev_b32_e32 v36, 12, v36
	v_lshl_add_u64 v[40:41], v[36:37], 0, v[18:19]
	global_load_dword v24, v[40:41], off
	v_add_u32_e32 v16, -5, v9
	v_lshlrev_b32_e32 v16, 12, v16
	v_lshl_add_u64 v[38:39], v[16:17], 0, v[18:19]
	global_load_dword v25, v[38:39], off
	v_add_u32_e32 v36, -6, v9
	v_lshlrev_b32_e32 v36, 12, v36
	v_lshl_add_u64 v[40:41], v[36:37], 0, v[18:19]
	global_load_dword v26, v[40:41], off
	v_add_u32_e32 v16, -7, v9
	v_lshlrev_b32_e32 v16, 12, v16
	v_lshl_add_u64 v[38:39], v[16:17], 0, v[18:19]
	global_load_dword v27, v[38:39], off
	s_cmp_lt_u32 s14, 3
	s_cbranch_scc1 .Lpq_issued
	v_add_u32_e32 v36, -8, v9
	v_lshlrev_b32_e32 v36, 12, v36
	v_lshl_add_u64 v[40:41], v[36:37], 0, v[18:19]
	global_load_dword v28, v[40:41], off
	v_add_u32_e32 v16, -9, v9
	v_lshlrev_b32_e32 v16, 12, v16
	v_lshl_add_u64 v[38:39], v[16:17], 0, v[18:19]
	global_load_dword v29, v[38:39], off
	v_add_u32_e32 v36, -10, v9
	v_lshlrev_b32_e32 v36, 12, v36
	v_lshl_add_u64 v[40:41], v[36:37], 0, v[18:19]
	global_load_dword v30, v[40:41], off
	v_add_u32_e32 v16, -11, v9
	v_lshlrev_b32_e32 v16, 12, v16
	v_lshl_add_u64 v[38:39], v[16:17], 0, v[18:19]
	global_load_dword v31, v[38:39], off
	v_add_u32_e32 v36, -12, v9
	v_lshlrev_b32_e32 v36, 12, v36
	v_lshl_add_u64 v[40:41], v[36:37], 0, v[18:19]
	global_load_dword v32, v[40:41], off
	v_add_u32_e32 v16, -13, v9
	v_lshlrev_b32_e32 v16, 12, v16
	v_lshl_add_u64 v[38:39], v[16:17], 0, v[18:19]
	global_load_dword v33, v[38:39], off
	v_add_u32_e32 v36, -14, v9
	v_lshlrev_b32_e32 v36, 12, v36
	v_lshl_add_u64 v[40:41], v[36:37], 0, v[18:19]
	global_load_dword v34, v[40:41], off
	v_add_u32_e32 v16, -15, v9
	v_lshlrev_b32_e32 v16, 12, v16
	v_lshl_add_u64 v[38:39], v[16:17], 0, v[18:19]
	global_load_dword v35, v[38:39], off
.Lpq_issued:
	s_waitcnt vmcnt(0)
	v_add_f32_e32 v14, 0, v20
	v_add_f32_e32 v14, v14, v21
	s_cmp_eq_u32 s14, 0
	s_cbranch_scc1 .Lpq_summed
	v_add_f32_e32 v14, v14, v22
	v_add_f32_e32 v14, v14, v23
	s_cmp_lt_u32 s14, 2
	s_cbranch_scc1 .Lpq_summed
	v_add_f32_e32 v14, v14, v24
	v_add_f32_e32 v14, v14, v25
	v_add_f32_e32 v14, v14, v26
	v_add_f32_e32 v14, v14, v27
	s_cmp_lt_u32 s14, 3
	s_cbranch_scc1 .Lpq_summed
	v_add_f32_e32 v14, v14, v28
	v_add_f32_e32 v14, v14, v29
	v_add_f32_e32 v14, v14, v30
	v_add_f32_e32 v14, v14, v31
	v_add_f32_e32 v14, v14, v32
	v_add_f32_e32 v14, v14, v33
	v_add_f32_e32 v14, v14, v34
	v_add_f32_e32 v14, v14, v35
.Lpq_summed:
	v_bfe_u32 v12, v7, 8, 2
	v_mov_b32_e32 v5, v20
	s_movk_i32 s0, 0x7fff
	v_lshlrev_b32_e64 v0, v12, 2
	v_cvt_f32_ubyte0_e32 v0, v0
	v_div_scale_f32 v6, s[12:13], v0, v0, v14
	v_rcp_f32_e32 v7, v6
	v_div_scale_f32 v8, vcc, v14, v0, v14
	s_nop 0
	v_fma_f32 v9, -v6, v7, 1.0
	v_fmac_f32_e32 v7, v9, v7
	v_mul_f32_e32 v9, v8, v7
	v_fma_f32 v10, -v6, v9, v8
	v_fmac_f32_e32 v9, v10, v7
	v_fma_f32 v6, -v6, v9, v8
	v_div_fmas_f32 v6, v6, v7, v9
	v_div_fixup_f32 v0, v6, v0, v14
	v_sub_f32_e32 v0, v0, v5
	v_bfe_u32 v5, v0, 16, 1
	v_add3_u32 v6, v0, v5, s0
	v_lshlrev_b32_e32 v0, 5, v12
	v_ashrrev_i32_e32 v5, 31, v4
	v_lshl_add_u64 v[4:5], v[0:1], 0, v[4:5]
	v_lshlrev_b64 v[4:5], 9, v[4:5]
	v_lshl_add_u64 v[4:5], v[2:3], 0, v[4:5]
	global_store_short_d16_hi v[4:5], v6, off sc1
